# GEMM epilogue de-serialisation: out-proj residual rows of both halves requested together; in-proj rope cos/sin loads issued under one predicate with one wait instead of a 4-step ladder
# speedup vs baseline: 1.0037x; 1.0011x over previous
.LBB0_202:
	s_add_i32 s24, s92, s53
	s_and_b32 s14, s24, -4
	s_cmp_lg_u32 s14, 4
	s_cselect_b64 s[14:15], -1, 0
	v_add_u32_e32 v186, s62, v194
	s_and_b64 s[14:15], s[36:37], s[14:15]
	s_and_b64 s[22:23], s[14:15], s[4:5]
	v_lshlrev_b32_e32 v181, 3, v186
	v_mov_b32_e32 v164, 1.0
	v_mov_b32_e32 v165, 1.0
	v_mov_b32_e32 v166, 1.0
	v_mov_b32_e32 v167, 1.0
	v_mov_b32_e32 v168, 1.0
	v_mov_b32_e32 v169, 1.0
	v_mov_b32_e32 v170, 1.0
	v_mov_b32_e32 v171, 1.0
	v_mov_b32_e32 v172, 1.0
	v_mov_b32_e32 v173, 1.0
	v_mov_b32_e32 v174, 1.0
	v_mov_b32_e32 v175, 1.0
	v_mov_b32_e32 v160, 1.0
	v_mov_b32_e32 v161, 1.0
	v_mov_b32_e32 v162, 1.0
	v_mov_b32_e32 v163, 1.0
	v_mov_b32_e32 v0, 0
	v_mov_b32_e32 v1, 0
	v_mov_b32_e32 v2, 0
	v_mov_b32_e32 v3, 0
	v_mov_b32_e32 v4, 0
	v_mov_b32_e32 v5, 0
	v_mov_b32_e32 v6, 0
	v_mov_b32_e32 v7, 0
	v_mov_b32_e32 v8, 0
	v_mov_b32_e32 v9, 0
	v_mov_b32_e32 v10, 0
	v_mov_b32_e32 v11, 0
	v_mov_b32_e32 v12, 0
	v_mov_b32_e32 v13, 0
	v_mov_b32_e32 v14, 0
	v_mov_b32_e32 v15, 0
	s_and_saveexec_b64 s[14:15], s[22:23]
	s_cbranch_execz .Lrope0_skip
	v_mov_b32_e32 v17, v213
	v_and_b32_e32 v16, 0xfff8, v181
	v_lshlrev_b32_e32 v16, 2, v16
	v_lshl_add_u64 v[18:19], v[182:183], 0, v[16:17]
	v_lshl_add_u64 v[20:21], v[184:185], 0, v[16:17]
	global_load_dwordx4 v[164:167], v[18:19], off
	global_load_dwordx4 v[0:3], v[20:21], off
	v_add_u32_e32 v16, 0x80, v181
	v_and_b32_e32 v16, 0xfff8, v16
	v_lshlrev_b32_e32 v16, 2, v16
	v_lshl_add_u64 v[18:19], v[182:183], 0, v[16:17]
	v_lshl_add_u64 v[20:21], v[184:185], 0, v[16:17]
	global_load_dwordx4 v[168:171], v[18:19], off
	global_load_dwordx4 v[4:7], v[20:21], off
	v_add_u32_e32 v16, 0x100, v181
	v_and_b32_e32 v16, 0xfff8, v16
	v_lshlrev_b32_e32 v16, 2, v16
	v_lshl_add_u64 v[18:19], v[182:183], 0, v[16:17]
	v_lshl_add_u64 v[20:21], v[184:185], 0, v[16:17]
	global_load_dwordx4 v[172:175], v[18:19], off
	global_load_dwordx4 v[8:11], v[20:21], off
	v_add_u32_e32 v16, 0x180, v181
	v_and_b32_e32 v16, 0xfff8, v16
	v_lshlrev_b32_e32 v16, 2, v16
	v_lshl_add_u64 v[18:19], v[182:183], 0, v[16:17]
	v_lshl_add_u64 v[20:21], v[184:185], 0, v[16:17]
	global_load_dwordx4 v[160:163], v[18:19], off
	global_load_dwordx4 v[12:15], v[20:21], off
.Lrope0_skip:
	s_or_b64 exec, exec, s[14:15]
	s_waitcnt vmcnt(0)
	s_cmp_lt_i32 s24, 8
	s_mov_b32 s14, 0x26000000
	s_cselect_b32 s14, s14, 0x29000000
	s_cmp_gt_i32 s24, 7
	s_cselect_b64 vcc, -1, 0
	s_cmp_gt_i32 s24, 3
	s_cselect_b32 s14, s14, 0x24000000
	s_lshl_b32 s14, s14, 1
	v_mov_b32_e32 v17, 0x3e38aa3b
	s_add_u32 s14, s30, s14
	v_cndmask_b32_e32 v188, 1.0, v17, vcc
	s_addc_u32 s15, s31, 0
	s_lshl_b32 s24, s92, 8
	s_and_b32 s24, s24, 0x300
	v_pk_mul_f32 v[24:25], v[188:189], v[2:3] op_sel_hi:[0,1]
	v_pk_mul_f32 v[26:27], v[188:189], v[0:1] op_sel_hi:[0,1]
	v_or_b32_e32 v17, s24, v196
	v_pk_mul_f32 v[20:21], v[188:189], v[166:167] op_sel_hi:[0,1]
	v_pk_mul_f32 v[22:23], v[188:189], v[164:165] op_sel_hi:[0,1]
	v_pk_mul_f32 v[0:1], v[154:155], v[24:25]
	v_pk_mul_f32 v[2:3], v[152:153], v[26:27]
	v_lshlrev_b32_e32 v18, 1, v17
	v_mov_b32_e32 v19, v213
	v_ashrrev_i32_e32 v187, 31, v186
	v_pk_fma_f32 v[28:29], v[158:159], v[20:21], v[0:1] neg_lo:[0,0,1] neg_hi:[0,0,1]
	v_pk_fma_f32 v[0:1], v[156:157], v[22:23], v[2:3] neg_lo:[0,0,1] neg_hi:[0,0,1]
	v_pk_mul_f32 v[2:3], v[154:155], v[20:21]
	v_pk_mul_f32 v[30:31], v[152:153], v[22:23]
	v_lshl_add_u64 v[190:191], s[14:15], 0, v[18:19]
	v_lshlrev_b64 v[18:19], 11, v[186:187]
	v_pk_fma_f32 v[152:153], v[158:159], v[24:25], v[2:3]
	v_pk_fma_f32 v[2:3], v[156:157], v[26:27], v[30:31]
	v_lshl_add_u64 v[18:19], v[190:191], 0, v[18:19]
	v_cvt_pk_bf16_f32 v0, v0, v1
	v_cvt_pk_bf16_f32 v1, v28, v29
	v_cvt_pk_bf16_f32 v2, v2, v3
	v_cvt_pk_bf16_f32 v3, v152, v153
	global_store_dwordx4 v[18:19], v[0:3], off
	v_pk_mul_f32 v[6:7], v[188:189], v[6:7] op_sel_hi:[0,1]
	v_pk_mul_f32 v[4:5], v[188:189], v[4:5] op_sel_hi:[0,1]
	v_pk_mul_f32 v[0:1], v[146:147], v[24:25]
	v_pk_mul_f32 v[2:3], v[144:145], v[26:27]
	v_pk_fma_f32 v[28:29], v[150:151], v[20:21], v[0:1] neg_lo:[0,0,1] neg_hi:[0,0,1]
	v_pk_fma_f32 v[0:1], v[148:149], v[22:23], v[2:3] neg_lo:[0,0,1] neg_hi:[0,0,1]
	v_pk_mul_f32 v[2:3], v[146:147], v[20:21]
	v_pk_mul_f32 v[20:21], v[144:145], v[22:23]
	v_pk_fma_f32 v[22:23], v[150:151], v[24:25], v[2:3]
	v_pk_fma_f32 v[2:3], v[148:149], v[26:27], v[20:21]
	v_cvt_pk_bf16_f32 v0, v0, v1
	v_cvt_pk_bf16_f32 v1, v28, v29
	v_cvt_pk_bf16_f32 v2, v2, v3
	v_cvt_pk_bf16_f32 v3, v22, v23
	s_waitcnt vmcnt(1)
	v_pk_mul_f32 v[22:23], v[188:189], v[168:169] op_sel_hi:[0,1]
	global_store_dwordx4 v[18:19], v[0:3], off offset:256
	v_pk_mul_f32 v[24:25], v[188:189], v[170:171] op_sel_hi:[0,1]
	v_pk_mul_f32 v[26:27], v[136:137], v[22:23]
	v_pk_mul_f32 v[0:1], v[136:137], v[4:5]
	v_pk_mul_f32 v[2:3], v[138:139], v[6:7]
	v_pk_fma_f32 v[0:1], v[140:141], v[22:23], v[0:1] neg_lo:[0,0,1] neg_hi:[0,0,1]
	v_pk_fma_f32 v[2:3], v[142:143], v[24:25], v[2:3] neg_lo:[0,0,1] neg_hi:[0,0,1]
	v_pk_mul_f32 v[28:29], v[138:139], v[24:25]
	v_pk_fma_f32 v[26:27], v[140:141], v[4:5], v[26:27]
	v_pk_fma_f32 v[28:29], v[142:143], v[6:7], v[28:29]
	v_cvt_pk_bf16_f32 v0, v0, v1
	v_cvt_pk_bf16_f32 v1, v2, v3
	v_cvt_pk_bf16_f32 v2, v26, v27
	v_add_co_u32_e32 v26, vcc, s72, v18
	v_cvt_pk_bf16_f32 v3, v28, v29
	s_nop 0
	v_addc_co_u32_e32 v27, vcc, 0, v19, vcc
	global_store_dwordx4 v[26:27], v[0:3], off
	s_mov_b64 s[14:15], 0x8000
	v_lshl_add_u64 v[20:21], v[18:19], 0, s[14:15]
	v_pk_mul_f32 v[0:1], v[128:129], v[4:5]
	v_pk_mul_f32 v[2:3], v[130:131], v[6:7]
	v_pk_fma_f32 v[0:1], v[132:133], v[22:23], v[0:1] neg_lo:[0,0,1] neg_hi:[0,0,1]
	v_pk_fma_f32 v[2:3], v[134:135], v[24:25], v[2:3] neg_lo:[0,0,1] neg_hi:[0,0,1]
	v_pk_mul_f32 v[22:23], v[128:129], v[22:23]
	v_pk_mul_f32 v[24:25], v[130:131], v[24:25]
	v_pk_fma_f32 v[4:5], v[132:133], v[4:5], v[22:23]
	v_pk_fma_f32 v[6:7], v[134:135], v[6:7], v[24:25]
	v_cvt_pk_bf16_f32 v0, v0, v1
	v_cvt_pk_bf16_f32 v1, v2, v3
	v_cvt_pk_bf16_f32 v2, v4, v5
	v_cvt_pk_bf16_f32 v3, v6, v7
	v_pk_mul_f32 v[6:7], v[188:189], v[172:173] op_sel_hi:[0,1]
	v_pk_mul_f32 v[10:11], v[188:189], v[10:11] op_sel_hi:[0,1]
	v_pk_mul_f32 v[8:9], v[188:189], v[8:9] op_sel_hi:[0,1]
	global_store_dwordx4 v[20:21], v[0:3], off offset:256
	v_pk_mul_f32 v[20:21], v[188:189], v[174:175] op_sel_hi:[0,1]
	v_pk_mul_f32 v[22:23], v[120:121], v[6:7]
	v_pk_mul_f32 v[0:1], v[120:121], v[8:9]
	v_pk_mul_f32 v[2:3], v[122:123], v[10:11]
	v_pk_fma_f32 v[0:1], v[124:125], v[6:7], v[0:1] neg_lo:[0,0,1] neg_hi:[0,0,1]
	v_pk_fma_f32 v[2:3], v[126:127], v[20:21], v[2:3] neg_lo:[0,0,1] neg_hi:[0,0,1]
	v_pk_mul_f32 v[24:25], v[122:123], v[20:21]
	v_pk_fma_f32 v[22:23], v[124:125], v[8:9], v[22:23]
	v_pk_fma_f32 v[24:25], v[126:127], v[10:11], v[24:25]
	v_cvt_pk_bf16_f32 v0, v0, v1
	v_cvt_pk_bf16_f32 v1, v2, v3
	v_cvt_pk_bf16_f32 v2, v22, v23
	v_add_co_u32_e32 v22, vcc, s89, v18
	v_cvt_pk_bf16_f32 v3, v24, v25
	s_nop 0
	v_addc_co_u32_e32 v23, vcc, 0, v19, vcc
	global_store_dwordx4 v[22:23], v[0:3], off
	s_mov_b64 s[14:15], 0x10000
	v_lshl_add_u64 v[4:5], v[18:19], 0, s[14:15]
	v_pk_mul_f32 v[0:1], v[112:113], v[8:9]
	v_pk_mul_f32 v[2:3], v[114:115], v[10:11]
	v_pk_fma_f32 v[0:1], v[116:117], v[6:7], v[0:1] neg_lo:[0,0,1] neg_hi:[0,0,1]
	v_pk_fma_f32 v[2:3], v[118:119], v[20:21], v[2:3] neg_lo:[0,0,1] neg_hi:[0,0,1]
	v_pk_mul_f32 v[6:7], v[112:113], v[6:7]
	v_pk_mul_f32 v[20:21], v[114:115], v[20:21]
	v_pk_fma_f32 v[6:7], v[116:117], v[8:9], v[6:7]
	v_pk_fma_f32 v[10:11], v[118:119], v[10:11], v[20:21]
	v_cvt_pk_bf16_f32 v0, v0, v1
	v_cvt_pk_bf16_f32 v1, v2, v3
	v_cvt_pk_bf16_f32 v2, v6, v7
	v_cvt_pk_bf16_f32 v3, v10, v11
	v_pk_mul_f32 v[6:7], v[188:189], v[160:161] op_sel_hi:[0,1]
	v_pk_mul_f32 v[10:11], v[188:189], v[14:15] op_sel_hi:[0,1]
	v_pk_mul_f32 v[12:13], v[188:189], v[12:13] op_sel_hi:[0,1]
	global_store_dwordx4 v[4:5], v[0:3], off offset:256
	v_pk_mul_f32 v[8:9], v[188:189], v[162:163] op_sel_hi:[0,1]
	v_pk_mul_f32 v[14:15], v[104:105], v[6:7]
	v_pk_mul_f32 v[0:1], v[104:105], v[12:13]
	v_pk_mul_f32 v[2:3], v[106:107], v[10:11]
	v_pk_fma_f32 v[0:1], v[108:109], v[6:7], v[0:1] neg_lo:[0,0,1] neg_hi:[0,0,1]
	v_pk_fma_f32 v[2:3], v[110:111], v[8:9], v[2:3] neg_lo:[0,0,1] neg_hi:[0,0,1]
	v_pk_mul_f32 v[20:21], v[106:107], v[8:9]
	v_pk_fma_f32 v[14:15], v[108:109], v[12:13], v[14:15]
	v_pk_fma_f32 v[20:21], v[110:111], v[10:11], v[20:21]
	v_cvt_pk_bf16_f32 v0, v0, v1
	v_cvt_pk_bf16_f32 v1, v2, v3
	v_cvt_pk_bf16_f32 v2, v14, v15
	v_add_co_u32_e32 v14, vcc, s93, v18
	v_cvt_pk_bf16_f32 v3, v20, v21
	s_nop 0
	v_addc_co_u32_e32 v15, vcc, 0, v19, vcc
	global_store_dwordx4 v[14:15], v[0:3], off
	s_mov_b64 s[14:15], 0x18000
	v_lshl_add_u64 v[4:5], v[18:19], 0, s[14:15]
	v_pk_mul_f32 v[0:1], v[96:97], v[12:13]
	v_pk_mul_f32 v[2:3], v[98:99], v[10:11]
	v_pk_fma_f32 v[0:1], v[100:101], v[6:7], v[0:1] neg_lo:[0,0,1] neg_hi:[0,0,1]
	v_pk_fma_f32 v[2:3], v[102:103], v[8:9], v[2:3] neg_lo:[0,0,1] neg_hi:[0,0,1]
	v_pk_mul_f32 v[6:7], v[96:97], v[6:7]
	v_pk_mul_f32 v[8:9], v[98:99], v[8:9]
	v_pk_fma_f32 v[6:7], v[100:101], v[12:13], v[6:7]
	v_pk_fma_f32 v[8:9], v[102:103], v[10:11], v[8:9]
	v_cvt_pk_bf16_f32 v0, v0, v1
	v_cvt_pk_bf16_f32 v1, v2, v3
	v_cvt_pk_bf16_f32 v2, v6, v7
	v_cvt_pk_bf16_f32 v3, v8, v9
	global_store_dwordx4 v[4:5], v[0:3], off offset:256
	v_mov_b32_e32 v16, 1.0
	v_mov_b32_e32 v8, 0
	v_mov_b32_e32 v24, 0
	v_mov_b32_e32 v25, 0
	v_mov_b32_e32 v26, 0
	v_mov_b32_e32 v27, 0
	v_mov_b32_e32 v28, 1.0
	v_mov_b32_e32 v29, 1.0
	v_mov_b32_e32 v30, 1.0
	v_mov_b32_e32 v31, 1.0
	s_and_saveexec_b64 s[14:15], s[22:23]
	s_cbranch_execz .LBB0_212
	v_add_u32_e32 v0, 0x400, v181
	v_and_b32_e32 v0, 0xfff8, v0
	v_lshlrev_b32_e32 v0, 2, v0
	v_mov_b32_e32 v1, v213
	v_lshl_add_u64 v[2:3], v[182:183], 0, v[0:1]
	v_lshl_add_u64 v[0:1], v[184:185], 0, v[0:1]
	global_load_dwordx4 v[28:31], v[2:3], off
	global_load_dwordx4 v[24:27], v[0:1], off

.LBB0_738:
	v_lshl_or_b32 v130, s57, 8, v174
	v_add_u32_e32 v128, s58, v172
	v_ashrrev_i32_e32 v131, 31, v130
	v_lshlrev_b64 v[154:155], 1, v[130:131]
	v_ashrrev_i32_e32 v129, 31, v128
	v_lshl_add_u64 v[156:157], s[10:11], 0, v[154:155]
	v_lshlrev_b64 v[158:159], 11, v[128:129]
	v_lshl_add_u64 v[128:129], v[156:157], 0, v[158:159]
	global_load_dwordx4 v[176:179], v[128:129], off
	global_load_dwordx4 v[180:183], v[128:129], off offset:256
	v_lshl_add_u64 v[164:165], v[158:159], 0, s[68:69]
	v_lshl_add_u64 v[128:129], v[156:157], 0, v[164:165]
	global_load_dwordx4 v[184:187], v[128:129], off
	global_load_dwordx4 v[144:147], v[128:129], off offset:256
	v_lshl_add_u64 v[162:163], v[158:159], 0, s[78:79]
	v_lshl_add_u64 v[128:129], v[156:157], 0, v[162:163]
	global_load_dwordx4 v[140:143], v[128:129], off
	global_load_dwordx4 v[136:139], v[128:129], off offset:256
	v_lshl_add_u64 v[160:161], v[158:159], 0, s[88:89]
	v_lshl_add_u64 v[128:129], v[156:157], 0, v[160:161]
	global_load_dwordx4 v[132:135], v[128:129], off
	s_nop 0
	global_load_dwordx4 v[128:131], v[128:129], off offset:256
	v_lshl_add_u64 v[228:229], v[158:159], 0, s[42:43]
	v_lshl_add_u64 v[228:229], v[156:157], 0, v[228:229]
	global_load_dwordx4 v[200:203], v[228:229], off
	global_load_dwordx4 v[204:207], v[228:229], off offset:256
	v_lshl_add_u64 v[228:229], v[158:159], 0, s[92:93]
	v_lshl_add_u64 v[228:229], v[156:157], 0, v[228:229]
	global_load_dwordx4 v[208:211], v[228:229], off
	global_load_dwordx4 v[216:219], v[228:229], off offset:256
	s_mov_b64 s[14:15], 0x50000
	v_lshl_add_u64 v[228:229], v[158:159], 0, s[14:15]
	v_lshl_add_u64 v[228:229], v[156:157], 0, v[228:229]
	global_load_dwordx4 v[220:223], v[228:229], off
	global_load_dwordx4 v[224:227], v[228:229], off offset:256
	s_mov_b64 s[14:15], 0x58000
	v_lshl_add_u64 v[228:229], v[158:159], 0, s[14:15]
	v_lshl_add_u64 v[228:229], v[156:157], 0, v[228:229]
	global_load_dwordx4 v[240:243], v[228:229], off
	global_load_dwordx4 v[244:247], v[228:229], off offset:256
	v_lshl_add_u64 v[192:193], s[12:13], 0, v[158:159]
	v_lshl_add_u64 v[192:193], v[192:193], 0, v[154:155]
	s_mov_b64 s[14:15], 0x50000
	s_andn2_b64 vcc, exec, s[2:3]
	s_waitcnt vmcnt(0)
	v_lshlrev_b32_e32 v188, 16, v176
	v_and_b32_e32 v189, 0xffff0000, v176
	v_lshlrev_b32_e32 v176, 16, v177
	v_and_b32_e32 v177, 0xffff0000, v177
	v_lshlrev_b32_e32 v190, 16, v178
	v_and_b32_e32 v191, 0xffff0000, v178
	v_lshlrev_b32_e32 v178, 16, v179
	v_and_b32_e32 v179, 0xffff0000, v179
	v_pk_fma_f32 v[126:127], v[176:177], s[80:81], v[126:127] op_sel_hi:[1,0,1]
	v_pk_fma_f32 v[124:125], v[188:189], s[80:81], v[124:125] op_sel_hi:[1,0,1]
	v_pk_fma_f32 v[176:177], v[178:179], s[80:81], v[122:123] op_sel_hi:[1,0,1]
	v_pk_fma_f32 v[122:123], v[190:191], s[80:81], v[120:121] op_sel_hi:[1,0,1]
	v_cvt_pk_bf16_f32 v120, v124, v125
	v_cvt_pk_bf16_f32 v121, v126, v127
	v_cvt_pk_bf16_f32 v122, v122, v123
	v_cvt_pk_bf16_f32 v123, v176, v177
	global_store_dwordx4 v[192:193], v[120:123], off
	v_lshlrev_b32_e32 v124, 16, v182
	v_and_b32_e32 v125, 0xffff0000, v182
	v_lshlrev_b32_e32 v120, 16, v180
	v_and_b32_e32 v121, 0xffff0000, v180
	v_lshlrev_b32_e32 v122, 16, v181
	v_and_b32_e32 v123, 0xffff0000, v181
	v_lshlrev_b32_e32 v126, 16, v183
	v_and_b32_e32 v127, 0xffff0000, v183
	v_pk_fma_f32 v[118:119], v[122:123], s[80:81], v[118:119] op_sel_hi:[1,0,1]
	v_pk_fma_f32 v[116:117], v[120:121], s[80:81], v[116:117] op_sel_hi:[1,0,1]
	v_pk_fma_f32 v[120:121], v[126:127], s[80:81], v[114:115] op_sel_hi:[1,0,1]
	v_pk_fma_f32 v[114:115], v[124:125], s[80:81], v[112:113] op_sel_hi:[1,0,1]
	v_cvt_pk_bf16_f32 v112, v116, v117
	v_cvt_pk_bf16_f32 v113, v118, v119
	v_cvt_pk_bf16_f32 v114, v114, v115
	v_cvt_pk_bf16_f32 v115, v120, v121
	global_store_dwordx4 v[192:193], v[112:115], off offset:256
	v_lshlrev_b32_e32 v116, 16, v185
	v_and_b32_e32 v117, 0xffff0000, v185
	v_lshlrev_b32_e32 v114, 16, v184
	v_and_b32_e32 v115, 0xffff0000, v184
	v_lshlrev_b32_e32 v118, 16, v186
	v_and_b32_e32 v119, 0xffff0000, v186
	v_lshlrev_b32_e32 v120, 16, v187
	v_and_b32_e32 v121, 0xffff0000, v187
	v_lshl_add_u64 v[112:113], s[12:13], 0, v[164:165]
	v_pk_fma_f32 v[110:111], v[116:117], s[80:81], v[110:111] op_sel_hi:[1,0,1]
	v_pk_fma_f32 v[108:109], v[114:115], s[80:81], v[108:109] op_sel_hi:[1,0,1]
	v_pk_fma_f32 v[114:115], v[120:121], s[80:81], v[106:107] op_sel_hi:[1,0,1]
	v_pk_fma_f32 v[106:107], v[118:119], s[80:81], v[104:105] op_sel_hi:[1,0,1]
	v_lshl_add_u64 v[112:113], v[112:113], 0, v[154:155]
	v_cvt_pk_bf16_f32 v104, v108, v109
	v_cvt_pk_bf16_f32 v105, v110, v111
	v_cvt_pk_bf16_f32 v106, v106, v107
	v_cvt_pk_bf16_f32 v107, v114, v115
	global_store_dwordx4 v[112:113], v[104:107], off
	v_lshlrev_b32_e32 v108, 16, v146
	v_and_b32_e32 v109, 0xffff0000, v146
	v_lshlrev_b32_e32 v104, 16, v144
	v_and_b32_e32 v105, 0xffff0000, v144
	v_lshlrev_b32_e32 v106, 16, v145
	v_and_b32_e32 v107, 0xffff0000, v145
	v_lshlrev_b32_e32 v110, 16, v147
	v_and_b32_e32 v111, 0xffff0000, v147
	v_pk_fma_f32 v[102:103], v[106:107], s[80:81], v[102:103] op_sel_hi:[1,0,1]
	v_pk_fma_f32 v[100:101], v[104:105], s[80:81], v[100:101] op_sel_hi:[1,0,1]
	v_pk_fma_f32 v[104:105], v[110:111], s[80:81], v[98:99] op_sel_hi:[1,0,1]
	v_pk_fma_f32 v[98:99], v[108:109], s[80:81], v[96:97] op_sel_hi:[1,0,1]
	v_cvt_pk_bf16_f32 v96, v100, v101
	v_cvt_pk_bf16_f32 v97, v102, v103
	v_cvt_pk_bf16_f32 v98, v98, v99
	v_cvt_pk_bf16_f32 v99, v104, v105
	global_store_dwordx4 v[112:113], v[96:99], off offset:256
	v_lshlrev_b32_e32 v100, 16, v142
	v_and_b32_e32 v101, 0xffff0000, v142
	v_lshlrev_b32_e32 v96, 16, v140
	v_and_b32_e32 v97, 0xffff0000, v140
	v_lshlrev_b32_e32 v98, 16, v141
	v_and_b32_e32 v99, 0xffff0000, v141
	v_lshlrev_b32_e32 v102, 16, v143
	v_and_b32_e32 v103, 0xffff0000, v143
	v_lshl_add_u64 v[104:105], s[12:13], 0, v[162:163]
	v_pk_fma_f32 v[94:95], v[98:99], s[80:81], v[94:95] op_sel_hi:[1,0,1]
	v_pk_fma_f32 v[92:93], v[96:97], s[80:81], v[92:93] op_sel_hi:[1,0,1]
	v_pk_fma_f32 v[96:97], v[102:103], s[80:81], v[90:91] op_sel_hi:[1,0,1]
	v_pk_fma_f32 v[90:91], v[100:101], s[80:81], v[88:89] op_sel_hi:[1,0,1]
	v_lshl_add_u64 v[104:105], v[104:105], 0, v[154:155]
	v_cvt_pk_bf16_f32 v88, v92, v93
	v_cvt_pk_bf16_f32 v89, v94, v95
	v_cvt_pk_bf16_f32 v90, v90, v91
	v_cvt_pk_bf16_f32 v91, v96, v97
	global_store_dwordx4 v[104:105], v[88:91], off
	v_lshlrev_b32_e32 v92, 16, v138
	v_and_b32_e32 v93, 0xffff0000, v138
	v_lshlrev_b32_e32 v88, 16, v136
	v_and_b32_e32 v89, 0xffff0000, v136
	v_lshlrev_b32_e32 v90, 16, v137
	v_and_b32_e32 v91, 0xffff0000, v137
	v_lshlrev_b32_e32 v94, 16, v139
	v_and_b32_e32 v95, 0xffff0000, v139
	v_pk_fma_f32 v[86:87], v[90:91], s[80:81], v[86:87] op_sel_hi:[1,0,1]
	v_pk_fma_f32 v[84:85], v[88:89], s[80:81], v[84:85] op_sel_hi:[1,0,1]
	v_pk_fma_f32 v[88:89], v[94:95], s[80:81], v[78:79] op_sel_hi:[1,0,1]
	v_pk_fma_f32 v[78:79], v[92:93], s[80:81], v[76:77] op_sel_hi:[1,0,1]
	v_cvt_pk_bf16_f32 v76, v84, v85
	v_cvt_pk_bf16_f32 v77, v86, v87
	v_cvt_pk_bf16_f32 v78, v78, v79
	v_cvt_pk_bf16_f32 v79, v88, v89
	global_store_dwordx4 v[104:105], v[76:79], off offset:256
	v_lshlrev_b32_e32 v84, 16, v134
	v_and_b32_e32 v85, 0xffff0000, v134
	v_lshlrev_b32_e32 v76, 16, v132
	v_and_b32_e32 v77, 0xffff0000, v132
	v_lshlrev_b32_e32 v78, 16, v133
	v_and_b32_e32 v79, 0xffff0000, v133
	v_lshlrev_b32_e32 v86, 16, v135
	v_and_b32_e32 v87, 0xffff0000, v135
	v_lshl_add_u64 v[88:89], s[12:13], 0, v[160:161]
	v_pk_fma_f32 v[78:79], v[78:79], s[80:81], v[82:83] op_sel_hi:[1,0,1]
	v_pk_fma_f32 v[76:77], v[76:77], s[80:81], v[80:81] op_sel_hi:[1,0,1]
	v_pk_fma_f32 v[80:81], v[86:87], s[80:81], v[74:75] op_sel_hi:[1,0,1]
	v_pk_fma_f32 v[74:75], v[84:85], s[80:81], v[72:73] op_sel_hi:[1,0,1]
	v_lshl_add_u64 v[88:89], v[88:89], 0, v[154:155]
	v_cvt_pk_bf16_f32 v72, v76, v77
	v_cvt_pk_bf16_f32 v73, v78, v79
	v_cvt_pk_bf16_f32 v74, v74, v75
	v_cvt_pk_bf16_f32 v75, v80, v81
	global_store_dwordx4 v[88:89], v[72:75], off
	v_lshlrev_b32_e32 v76, 16, v130
	v_and_b32_e32 v77, 0xffff0000, v130
	v_lshlrev_b32_e32 v72, 16, v128
	v_and_b32_e32 v73, 0xffff0000, v128
	v_lshlrev_b32_e32 v74, 16, v129
	v_and_b32_e32 v75, 0xffff0000, v129
	v_lshlrev_b32_e32 v78, 16, v131
	v_and_b32_e32 v79, 0xffff0000, v131
	v_pk_fma_f32 v[70:71], v[74:75], s[80:81], v[70:71] op_sel_hi:[1,0,1]
	v_pk_fma_f32 v[68:69], v[72:73], s[80:81], v[68:69] op_sel_hi:[1,0,1]
	v_pk_fma_f32 v[72:73], v[78:79], s[80:81], v[66:67] op_sel_hi:[1,0,1]
	v_pk_fma_f32 v[66:67], v[76:77], s[80:81], v[64:65] op_sel_hi:[1,0,1]
	v_cvt_pk_bf16_f32 v64, v68, v69
	v_cvt_pk_bf16_f32 v65, v70, v71
	v_cvt_pk_bf16_f32 v66, v66, v67
	v_cvt_pk_bf16_f32 v67, v72, v73
	global_store_dwordx4 v[88:89], v[64:67], off offset:256
	v_lshl_add_u64 v[96:97], v[158:159], 0, s[42:43]
	v_lshl_add_u64 v[98:99], v[158:159], 0, s[92:93]
	v_lshl_add_u64 v[100:101], v[158:159], 0, s[14:15]
	s_mov_b64 s[14:15], 0x58000
	v_lshl_add_u64 v[102:103], v[158:159], 0, s[14:15]
	v_lshl_add_u64 v[96:97], s[12:13], 0, v[96:97]
	v_lshl_add_u64 v[96:97], v[96:97], 0, v[154:155]
	s_mov_b64 s[14:15], -1
	v_mov_b64_e32 v[68:69], v[204:205]
	v_mov_b64_e32 v[70:71], v[206:207]
	v_mov_b64_e32 v[72:73], v[208:209]
	v_mov_b64_e32 v[74:75], v[210:211]
	v_mov_b64_e32 v[76:77], v[216:217]
	v_mov_b64_e32 v[78:79], v[218:219]
	v_mov_b64_e32 v[80:81], v[220:221]
	v_mov_b64_e32 v[82:83], v[222:223]
	v_mov_b64_e32 v[84:85], v[224:225]
	v_mov_b64_e32 v[86:87], v[226:227]
	v_mov_b64_e32 v[88:89], v[240:241]
	v_mov_b64_e32 v[90:91], v[242:243]
	v_mov_b64_e32 v[92:93], v[244:245]
	v_mov_b64_e32 v[94:95], v[246:247]
	v_mov_b64_e32 v[64:65], v[200:201]
	v_mov_b64_e32 v[66:67], v[202:203]
	v_lshlrev_b32_e32 v104, 16, v64
	v_and_b32_e32 v105, 0xffff0000, v64
	v_lshlrev_b32_e32 v64, 16, v65
	v_and_b32_e32 v65, 0xffff0000, v65
	v_lshlrev_b32_e32 v106, 16, v66
	v_and_b32_e32 v107, 0xffff0000, v66
	v_lshlrev_b32_e32 v66, 16, v67
	v_and_b32_e32 v67, 0xffff0000, v67
	v_pk_fma_f32 v[62:63], v[64:65], s[80:81], v[62:63] op_sel_hi:[1,0,1]
	v_pk_fma_f32 v[60:61], v[104:105], s[80:81], v[60:61] op_sel_hi:[1,0,1]
	v_pk_fma_f32 v[64:65], v[66:67], s[80:81], v[58:59] op_sel_hi:[1,0,1]
	v_pk_fma_f32 v[58:59], v[106:107], s[80:81], v[56:57] op_sel_hi:[1,0,1]
	v_cvt_pk_bf16_f32 v56, v60, v61
	v_cvt_pk_bf16_f32 v57, v62, v63
	v_cvt_pk_bf16_f32 v58, v58, v59
	v_cvt_pk_bf16_f32 v59, v64, v65
	global_store_dwordx4 v[96:97], v[56:59], off
	v_lshlrev_b32_e32 v60, 16, v70
	v_and_b32_e32 v61, 0xffff0000, v70
	v_lshlrev_b32_e32 v56, 16, v68
	v_and_b32_e32 v57, 0xffff0000, v68
	v_lshlrev_b32_e32 v58, 16, v69
	v_and_b32_e32 v59, 0xffff0000, v69
	v_lshlrev_b32_e32 v62, 16, v71
	v_and_b32_e32 v63, 0xffff0000, v71
	v_pk_fma_f32 v[54:55], v[58:59], s[80:81], v[54:55] op_sel_hi:[1,0,1]
	v_pk_fma_f32 v[52:53], v[56:57], s[80:81], v[52:53] op_sel_hi:[1,0,1]
	v_pk_fma_f32 v[56:57], v[62:63], s[80:81], v[46:47] op_sel_hi:[1,0,1]
	v_pk_fma_f32 v[46:47], v[60:61], s[80:81], v[44:45] op_sel_hi:[1,0,1]
	v_cvt_pk_bf16_f32 v44, v52, v53
	v_cvt_pk_bf16_f32 v45, v54, v55
	v_cvt_pk_bf16_f32 v46, v46, v47
	v_cvt_pk_bf16_f32 v47, v56, v57
	global_store_dwordx4 v[96:97], v[44:47], off offset:256
	v_lshlrev_b32_e32 v52, 16, v74
	v_and_b32_e32 v53, 0xffff0000, v74
	v_lshlrev_b32_e32 v44, 16, v72
	v_and_b32_e32 v45, 0xffff0000, v72
	v_lshlrev_b32_e32 v46, 16, v73
	v_and_b32_e32 v47, 0xffff0000, v73
	v_lshlrev_b32_e32 v54, 16, v75
	v_and_b32_e32 v55, 0xffff0000, v75
	v_lshl_add_u64 v[56:57], s[12:13], 0, v[98:99]
	v_pk_fma_f32 v[46:47], v[46:47], s[80:81], v[50:51] op_sel_hi:[1,0,1]
	v_pk_fma_f32 v[44:45], v[44:45], s[80:81], v[48:49] op_sel_hi:[1,0,1]
	v_pk_fma_f32 v[48:49], v[54:55], s[80:81], v[42:43] op_sel_hi:[1,0,1]
	v_pk_fma_f32 v[42:43], v[52:53], s[80:81], v[40:41] op_sel_hi:[1,0,1]
	v_lshl_add_u64 v[56:57], v[56:57], 0, v[154:155]
	v_cvt_pk_bf16_f32 v40, v44, v45
	v_cvt_pk_bf16_f32 v41, v46, v47
	v_cvt_pk_bf16_f32 v42, v42, v43
	v_cvt_pk_bf16_f32 v43, v48, v49
	global_store_dwordx4 v[56:57], v[40:43], off
	v_lshlrev_b32_e32 v44, 16, v78
	v_and_b32_e32 v45, 0xffff0000, v78
	v_lshlrev_b32_e32 v40, 16, v76
	v_and_b32_e32 v41, 0xffff0000, v76
	v_lshlrev_b32_e32 v42, 16, v77
	v_and_b32_e32 v43, 0xffff0000, v77
	v_lshlrev_b32_e32 v46, 16, v79
	v_and_b32_e32 v47, 0xffff0000, v79
	v_pk_fma_f32 v[38:39], v[42:43], s[80:81], v[38:39] op_sel_hi:[1,0,1]
	v_pk_fma_f32 v[36:37], v[40:41], s[80:81], v[36:37] op_sel_hi:[1,0,1]
	v_pk_fma_f32 v[40:41], v[46:47], s[80:81], v[30:31] op_sel_hi:[1,0,1]
	v_pk_fma_f32 v[30:31], v[44:45], s[80:81], v[28:29] op_sel_hi:[1,0,1]
	v_cvt_pk_bf16_f32 v28, v36, v37
	v_cvt_pk_bf16_f32 v29, v38, v39
	v_cvt_pk_bf16_f32 v30, v30, v31
	v_cvt_pk_bf16_f32 v31, v40, v41
	global_store_dwordx4 v[56:57], v[28:31], off offset:256
	v_lshlrev_b32_e32 v36, 16, v82
	v_and_b32_e32 v37, 0xffff0000, v82
	v_lshlrev_b32_e32 v28, 16, v80
	v_and_b32_e32 v29, 0xffff0000, v80
	v_lshlrev_b32_e32 v30, 16, v81
	v_and_b32_e32 v31, 0xffff0000, v81
	v_lshlrev_b32_e32 v38, 16, v83
	v_and_b32_e32 v39, 0xffff0000, v83
	v_lshl_add_u64 v[40:41], s[12:13], 0, v[100:101]
	v_pk_fma_f32 v[30:31], v[30:31], s[80:81], v[34:35] op_sel_hi:[1,0,1]
	v_pk_fma_f32 v[28:29], v[28:29], s[80:81], v[32:33] op_sel_hi:[1,0,1]
	v_pk_fma_f32 v[32:33], v[38:39], s[80:81], v[26:27] op_sel_hi:[1,0,1]
	v_pk_fma_f32 v[26:27], v[36:37], s[80:81], v[24:25] op_sel_hi:[1,0,1]
	v_lshl_add_u64 v[40:41], v[40:41], 0, v[154:155]
	v_cvt_pk_bf16_f32 v24, v28, v29
	v_cvt_pk_bf16_f32 v25, v30, v31
	v_cvt_pk_bf16_f32 v26, v26, v27
	v_cvt_pk_bf16_f32 v27, v32, v33
	global_store_dwordx4 v[40:41], v[24:27], off
	v_lshlrev_b32_e32 v28, 16, v86
	v_and_b32_e32 v29, 0xffff0000, v86
	v_lshlrev_b32_e32 v24, 16, v84
	v_and_b32_e32 v25, 0xffff0000, v84
	v_lshlrev_b32_e32 v26, 16, v85
	v_and_b32_e32 v27, 0xffff0000, v85
	v_lshlrev_b32_e32 v30, 16, v87
	v_and_b32_e32 v31, 0xffff0000, v87
	v_pk_fma_f32 v[22:23], v[26:27], s[80:81], v[22:23] op_sel_hi:[1,0,1]
	v_pk_fma_f32 v[20:21], v[24:25], s[80:81], v[20:21] op_sel_hi:[1,0,1]
	v_pk_fma_f32 v[24:25], v[30:31], s[80:81], v[14:15] op_sel_hi:[1,0,1]
	v_pk_fma_f32 v[14:15], v[28:29], s[80:81], v[12:13] op_sel_hi:[1,0,1]
	v_cvt_pk_bf16_f32 v12, v20, v21
	v_cvt_pk_bf16_f32 v13, v22, v23
	v_cvt_pk_bf16_f32 v14, v14, v15
	v_cvt_pk_bf16_f32 v15, v24, v25
	global_store_dwordx4 v[40:41], v[12:15], off offset:256
	v_lshlrev_b32_e32 v20, 16, v90
	v_and_b32_e32 v21, 0xffff0000, v90
	v_lshlrev_b32_e32 v12, 16, v88
	v_and_b32_e32 v13, 0xffff0000, v88
	v_lshlrev_b32_e32 v14, 16, v89
	v_and_b32_e32 v15, 0xffff0000, v89
	v_lshlrev_b32_e32 v22, 16, v91
	v_and_b32_e32 v23, 0xffff0000, v91
	v_lshl_add_u64 v[24:25], s[12:13], 0, v[102:103]
	v_pk_fma_f32 v[14:15], v[14:15], s[80:81], v[18:19] op_sel_hi:[1,0,1]
	v_pk_fma_f32 v[12:13], v[12:13], s[80:81], v[16:17] op_sel_hi:[1,0,1]
	v_pk_fma_f32 v[16:17], v[22:23], s[80:81], v[10:11] op_sel_hi:[1,0,1]
	v_pk_fma_f32 v[10:11], v[20:21], s[80:81], v[8:9] op_sel_hi:[1,0,1]
	v_lshl_add_u64 v[24:25], v[24:25], 0, v[154:155]
	v_cvt_pk_bf16_f32 v8, v12, v13
	v_cvt_pk_bf16_f32 v9, v14, v15
	v_cvt_pk_bf16_f32 v10, v10, v11
	v_cvt_pk_bf16_f32 v11, v16, v17
	global_store_dwordx4 v[24:25], v[8:11], off
	v_lshlrev_b32_e32 v12, 16, v94
	v_and_b32_e32 v13, 0xffff0000, v94
	v_lshlrev_b32_e32 v8, 16, v92
	v_and_b32_e32 v9, 0xffff0000, v92
	v_lshlrev_b32_e32 v10, 16, v93
	v_and_b32_e32 v11, 0xffff0000, v93
	v_lshlrev_b32_e32 v14, 16, v95
	v_and_b32_e32 v15, 0xffff0000, v95
	v_pk_fma_f32 v[6:7], v[10:11], s[80:81], v[6:7] op_sel_hi:[1,0,1]
	v_pk_fma_f32 v[4:5], v[8:9], s[80:81], v[4:5] op_sel_hi:[1,0,1]
	v_pk_fma_f32 v[8:9], v[14:15], s[80:81], v[2:3] op_sel_hi:[1,0,1]
	v_pk_fma_f32 v[2:3], v[12:13], s[80:81], v[0:1] op_sel_hi:[1,0,1]
	v_cvt_pk_bf16_f32 v0, v4, v5
	v_cvt_pk_bf16_f32 v1, v6, v7
	v_cvt_pk_bf16_f32 v2, v2, v3
	v_cvt_pk_bf16_f32 v3, v8, v9
	global_store_dwordx4 v[24:25], v[0:3], off offset:256
	s_cbranch_vccnz .LBB0_722
	s_andn2_b64 vcc, exec, s[8:9]
	s_cbranch_vccnz .LBB0_721
	s_barrier
	s_branch .LBB0_721
